# RG-LRU gate GEMM: all remaining operand fragments prefetched into VGPRs idle during the mixer phase (was read-wait-mfma per MFMA); on top of v58
# baseline (speedup 1.0000x reference)
; __device__ __forceinline__ float bf2f(bf16_t v) { return __uint_as_float(((unsigned)v) << 16); }
; __device__ __forceinline__ float sigmoidf_(float x) { return __builtin_amdgcn_rcpf(1.f + __expf(-x)); }
; #define MFMA16(a, b, c) __builtin_amdgcn_mfma_f32_16x16x32_bf16((a), (b), (c), 0, 0, 0)
; __device__ __forceinline__ void rglru_unit(const Params& p, const WS& ws, int j, int u, bool dry = false) {
;     ...
; #pragma unroll
;       for (int ks = 0; ks < 4; ++ks) {
;         const bf16x8 xf = *(const bf16x8*)(XC + (16 * w + lr) * 136 + 32 * ks + 8 * lq);
; #pragma unroll
;         for (int gate = 0; gate < 2; ++gate)
; #pragma unroll
;           for (int mt = 0; mt < 2; ++mt) {
;             const bf16x8 wf = *(const bf16x8*)(WG + (gate * 32 + 16 * mt + lr) * 136 + 32 * ks + 8 * lq);
;             ga_[gate][mt] = MFMA16(wf, xf, ga_[gate][mt]);
;           }
;       }
;       const int tok = 16 * w + lr;
; #pragma unroll
;       for (int mt = 0; mt < 2; ++mt)
; #pragma unroll
;         for (int jj = 0; jj < 4; ++jj) {
;           const int n = 16 * mt + 4 * lq + jj;
;           const float xcv = bf2f(XC[tok * 136 + 32 * jq + n]);
;           const float r = sigmoidf_(ga_[0][mt][jj] + ba[mt][jj]);
;           const float ig = sigmoidf_(ga_[1][mt][jj] + bx[mt][jj]);
;           const float la = -r * sp[mt][jj];
;           const float a = __expf(la);
;           const float x2 = 2.f * la;
;           const float om = x2 > -0.02f ? -x2 * (1.f + 0.5f * x2 * (1.f + x2 * (1.f / 3.f))) : 1.f - a * a;
;           const float mult = __builtin_amdgcn_sqrtf(fmaxf(om, 0.f));
;           AUa[tok * 33 + n] = a;
;           AUu[tok * 33 + n] = mult * ig * xcv;
;         }
.LBB0_1420:
	ds_read_b128 v[52:55], v111
	ds_read_b128 v[56:59], v112 offset:17408
	ds_read_b128 v[60:63], v112 offset:21760
	ds_read_b128 v[64:67], v112 offset:26112
	ds_read_b128 v[136:139], v112 offset:30464
	ds_read_b128 v[212:215], v111 offset:64
	ds_read_b128 v[216:219], v111 offset:128
	ds_read_b128 v[220:223], v111 offset:192
	ds_read_b128 v[224:227], v112 offset:17472
	ds_read_b128 v[228:231], v112 offset:21824
	ds_read_b128 v[232:235], v112 offset:26176
	ds_read_b128 v[244:247], v112 offset:30528
	ds_read_b128 v[248:251], v112 offset:17536
	ds_read_b128 v[252:255], v112 offset:21888
	s_waitcnt lgkmcnt(12)
	v_mfma_f32_16x16x32_bf16 v[56:59], v[56:59], v[52:55], 0
	s_waitcnt lgkmcnt(11)
	v_mfma_f32_16x16x32_bf16 v[60:63], v[60:63], v[52:55], 0
	s_waitcnt lgkmcnt(10)
	v_mfma_f32_16x16x32_bf16 v[64:67], v[64:67], v[52:55], 0
	s_waitcnt lgkmcnt(9)
	v_mfma_f32_16x16x32_bf16 v[52:55], v[136:139], v[52:55], 0
	s_nop 0
	s_nop 0
	s_waitcnt lgkmcnt(5)
	v_mfma_f32_16x16x32_bf16 v[56:59], v[224:227], v[212:215], v[56:59]
	ds_read_b128 v[224:227], v112 offset:26240
	s_nop 0
	s_waitcnt lgkmcnt(5)
	v_mfma_f32_16x16x32_bf16 v[60:63], v[228:231], v[212:215], v[60:63]
	ds_read_b128 v[228:231], v112 offset:30592
	s_nop 0
	s_waitcnt lgkmcnt(5)
	v_mfma_f32_16x16x32_bf16 v[64:67], v[232:235], v[212:215], v[64:67]
	ds_read_b128 v[232:235], v112 offset:17600
	s_nop 0
	s_waitcnt lgkmcnt(5)
	v_mfma_f32_16x16x32_bf16 v[52:55], v[244:247], v[212:215], v[52:55]
	ds_read_b128 v[244:247], v112 offset:21952
	s_nop 0
	s_nop 0
	s_waitcnt lgkmcnt(5)
	v_mfma_f32_16x16x32_bf16 v[56:59], v[248:251], v[216:219], v[56:59]
	ds_read_b128 v[248:251], v112 offset:26304
	s_nop 0
	s_waitcnt lgkmcnt(5)
	v_mfma_f32_16x16x32_bf16 v[60:63], v[252:255], v[216:219], v[60:63]
	ds_read_b128 v[252:255], v112 offset:30656
	s_nop 0
	s_waitcnt lgkmcnt(5)
	v_mfma_f32_16x16x32_bf16 v[140:143], v[224:227], v[216:219], v[64:67]
	s_nop 2
	s_nop 0
	s_waitcnt lgkmcnt(4)
	v_mfma_f32_16x16x32_bf16 v[52:55], v[228:231], v[216:219], v[52:55]
	s_nop 0
	s_nop 0
	ds_read_u16 v13, v113
	s_waitcnt lgkmcnt(4)
	v_mfma_f32_16x16x32_bf16 v[64:67], v[232:235], v[220:223], v[56:59]
	s_nop 2
	s_nop 0
	s_waitcnt lgkmcnt(3)
	v_mfma_f32_16x16x32_bf16 v[56:59], v[244:247], v[220:223], v[60:63]
	s_nop 2
	s_nop 0
	v_add_f32_e32 v14, v0, v64
	v_mul_f32_e32 v14, 0xbfb8aa3b, v14
	v_exp_f32_e32 v14, v14
	s_waitcnt lgkmcnt(2)
	v_mfma_f32_16x16x32_bf16 v[60:63], v[248:251], v[220:223], v[140:143]
	s_nop 2
	s_nop 0
	v_add_f32_e32 v14, 1.0, v14
	v_rcp_f32_e64 v14, -v14
	s_waitcnt lgkmcnt(0)
	v_mfma_f32_16x16x32_bf16 v[52:55], v[252:255], v[220:223], v[52:55]
	v_mul_f32_e32 v14, v89, v14
	v_mul_f32_e32 v15, 0x3fb8aa3b, v14
	v_exp_f32_e32 v15, v15
	v_add_f32_e32 v14, v14, v14
	v_cmp_nlt_f32_e64 s[52:53], s29, v14
	s_and_saveexec_b64 s[4:5], s[52:53]
	s_xor_b64 s[4:5], exec, s[4:5]
	v_fma_f32 v64, -v15, v15, 1.0
	s_andn2_saveexec_b64 s[4:5], s[4:5]
	v_pk_mul_f32 v[136:137], v[14:15], s[88:89] op_sel_hi:[0,1]
	v_add_f32_e32 v64, 1.0, v137
	v_fma_f32 v64, v136, v64, 1.0
	v_mul_f32_e64 v64, v64, -v14
	s_or_b64 exec, exec, s[4:5]
	v_add_f32_e32 v14, v8, v60
	v_max_f32_e32 v60, v64, v64
	v_add_f32_e32 v64, v1, v65
	v_mul_f32_e32 v14, 0xbfb8aa3b, v14
	v_mul_f32_e32 v64, 0xbfb8aa3b, v64
	v_exp_f32_e32 v14, v14
	v_exp_f32_e32 v64, v64
	v_max_f32_e32 v60, 0, v60
	v_sqrt_f32_e32 v60, v60
	v_add_f32_e32 v14, 1.0, v14
	v_add_f32_e32 v64, 1.0, v64
	v_rcp_f32_e32 v14, v14
	v_rcp_f32_e64 v64, -v64
	v_lshlrev_b32_e32 v13, 16, v13
	v_mul_f32_e32 v14, v14, v60
	v_mul_f32_e32 v64, v93, v64
	v_mul_f32_e32 v14, v14, v13
	ds_read_u16 v60, v113 offset:2
	v_mul_f32_e32 v13, 0x3fb8aa3b, v64
	v_exp_f32_e32 v13, v13
	ds_write2st64_b32 v72, v15, v14 offset0:136 offset1:169
	v_add_f32_e32 v14, v64, v64
	v_cmp_nlt_f32_e64 s[52:53], s29, v14
	s_and_saveexec_b64 s[4:5], s[52:53]
	s_xor_b64 s[4:5], exec, s[4:5]
	v_fma_f32 v15, -v13, v13, 1.0
	s_andn2_saveexec_b64 s[4:5], s[4:5]
	v_pk_mul_f32 v[64:65], v[14:15], s[88:89] op_sel_hi:[0,1]
	v_add_f32_e32 v15, 1.0, v65
	v_fma_f32 v15, v64, v15, 1.0
	v_mul_f32_e64 v15, v15, -v14
	s_or_b64 exec, exec, s[4:5]
	s_waitcnt lgkmcnt(1)
	v_lshlrev_b32_e32 v14, 16, v60
	v_add_f32_e32 v60, v9, v61
	v_mul_f32_e32 v60, 0xbfb8aa3b, v60
	v_exp_f32_e32 v60, v60
	v_max_f32_e32 v15, v15, v15
	v_max_f32_e32 v15, 0, v15
	v_sqrt_f32_e32 v15, v15
	v_add_f32_e32 v60, 1.0, v60
	v_rcp_f32_e32 v60, v60
	v_add_u32_e32 v135, 4, v72
	v_mul_f32_e32 v15, v60, v15
	v_mul_f32_e32 v14, v15, v14
	ds_write2st64_b32 v135, v13, v14 offset0:136 offset1:169
	v_add_f32_e32 v14, v2, v66
	v_mul_f32_e32 v14, 0xbfb8aa3b, v14
	v_exp_f32_e32 v14, v14
	ds_read_u16 v13, v113 offset:4
	v_add_f32_e32 v14, 1.0, v14
	v_rcp_f32_e64 v14, -v14
	s_nop 0
	v_mul_f32_e32 v14, v95, v14
	v_mul_f32_e32 v15, 0x3fb8aa3b, v14
	v_exp_f32_e32 v15, v15
	v_add_f32_e32 v14, v14, v14
	v_cmp_nlt_f32_e64 s[52:53], s29, v14
	s_and_saveexec_b64 s[4:5], s[52:53]
	s_xor_b64 s[4:5], exec, s[4:5]
	v_fma_f32 v60, -v15, v15, 1.0
	s_andn2_saveexec_b64 s[4:5], s[4:5]
	v_pk_mul_f32 v[60:61], v[14:15], s[88:89] op_sel_hi:[0,1]
	v_add_f32_e32 v61, 1.0, v61
	v_fma_f32 v60, v60, v61, 1.0
	v_mul_f32_e64 v60, v60, -v14
	s_or_b64 exec, exec, s[4:5]
	v_add_f32_e32 v14, v10, v62
	v_mul_f32_e32 v14, 0xbfb8aa3b, v14
	v_exp_f32_e32 v14, v14
	v_max_f32_e32 v60, v60, v60
	v_max_f32_e32 v60, 0, v60
	v_sqrt_f32_e32 v60, v60
	v_add_f32_e32 v14, 1.0, v14
	v_rcp_f32_e32 v14, v14
	s_waitcnt lgkmcnt(0)
; __device__ __forceinline__ float bf2f(bf16_t v) { return __uint_as_float(((unsigned)v) << 16); }
; __device__ __forceinline__ float sigmoidf_(float x) { return __builtin_amdgcn_rcpf(1.f + __expf(-x)); }
; __device__ __forceinline__ void rglru_unit(const Params& p, const WS& ws, int j, int u, bool dry = false) {
;     ...
; #pragma unroll
;       for (int mt = 0; mt < 2; ++mt)
; #pragma unroll
;         for (int jj = 0; jj < 4; ++jj) {
;           const int n = 16 * mt + 4 * lq + jj;
;           const float xcv = bf2f(XC[tok * 136 + 32 * jq + n]);
;           const float r = sigmoidf_(ga_[0][mt][jj] + ba[mt][jj]);
;           const float ig = sigmoidf_(ga_[1][mt][jj] + bx[mt][jj]);
;           const float la = -r * sp[mt][jj];
;           const float a = __expf(la);
;           const float x2 = 2.f * la;
;           const float om = x2 > -0.02f ? -x2 * (1.f + 0.5f * x2 * (1.f + x2 * (1.f / 3.f))) : 1.f - a * a;
;           const float mult = __builtin_amdgcn_sqrtf(fmaxf(om, 0.f));
;           AUa[tok * 33 + n] = a;
;           AUu[tok * 33 + n] = mult * ig * xcv;
;         }
;     }
;     __syncthreads();
	v_lshlrev_b32_e32 v13, 16, v13
	v_add_u32_e32 v136, 8, v72
	v_mul_f32_e32 v14, v14, v60
	v_mul_f32_e32 v13, v14, v13
	v_add_f32_e32 v14, v3, v67
	v_mul_f32_e32 v14, 0xbfb8aa3b, v14
	v_exp_f32_e32 v14, v14
	ds_write2st64_b32 v136, v15, v13 offset0:136 offset1:169
	ds_read_u16 v13, v113 offset:6
	v_add_f32_e32 v14, 1.0, v14
	v_rcp_f32_e64 v14, -v14
	s_nop 0
	v_mul_f32_e32 v14, v96, v14
	v_mul_f32_e32 v15, 0x3fb8aa3b, v14
	v_exp_f32_e32 v15, v15
	v_add_f32_e32 v14, v14, v14
	v_cmp_nlt_f32_e64 s[52:53], s29, v14
	s_and_saveexec_b64 s[4:5], s[52:53]
	s_xor_b64 s[4:5], exec, s[4:5]
	v_fma_f32 v60, -v15, v15, 1.0
	s_andn2_saveexec_b64 s[4:5], s[4:5]
	v_pk_mul_f32 v[60:61], v[14:15], s[88:89] op_sel_hi:[0,1]
	v_add_f32_e32 v61, 1.0, v61
	v_fma_f32 v60, v60, v61, 1.0
	v_mul_f32_e64 v60, v60, -v14
	s_or_b64 exec, exec, s[4:5]
	v_add_f32_e32 v14, v11, v63
	v_mul_f32_e32 v14, 0xbfb8aa3b, v14
	v_exp_f32_e32 v14, v14
	v_max_f32_e32 v60, v60, v60
	v_max_f32_e32 v60, 0, v60
	v_sqrt_f32_e32 v60, v60
	v_add_f32_e32 v14, 1.0, v14
	v_rcp_f32_e32 v14, v14
	s_waitcnt lgkmcnt(0)
	v_lshlrev_b32_e32 v13, 16, v13
	v_add_u32_e32 v139, 12, v72
	v_mul_f32_e32 v14, v14, v60
	v_mul_f32_e32 v13, v14, v13
	v_add_f32_e32 v14, v4, v56
	v_mul_f32_e32 v14, 0xbfb8aa3b, v14
	v_exp_f32_e32 v14, v14
	ds_write2st64_b32 v139, v15, v13 offset0:136 offset1:169
	ds_read_u16 v13, v113 offset:32
	v_add_f32_e32 v14, 1.0, v14
	v_rcp_f32_e64 v14, -v14
	s_nop 0
	v_mul_f32_e32 v14, v97, v14
	v_mul_f32_e32 v15, 0x3fb8aa3b, v14
	v_exp_f32_e32 v15, v15
	v_add_f32_e32 v14, v14, v14
	v_cmp_nlt_f32_e64 s[52:53], s29, v14
	s_and_saveexec_b64 s[4:5], s[52:53]
	s_xor_b64 s[4:5], exec, s[4:5]
	v_fma_f32 v56, -v15, v15, 1.0
	s_andn2_saveexec_b64 s[4:5], s[4:5]
	v_pk_mul_f32 v[60:61], v[14:15], s[88:89] op_sel_hi:[0,1]
	v_add_f32_e32 v56, 1.0, v61
	v_fma_f32 v56, v60, v56, 1.0
	v_mul_f32_e64 v56, v56, -v14
	s_or_b64 exec, exec, s[4:5]
	v_add_f32_e32 v14, v16, v52
	v_mul_f32_e32 v14, 0xbfb8aa3b, v14
	v_exp_f32_e32 v14, v14
	v_max_f32_e32 v52, v56, v56
	v_max_f32_e32 v52, 0, v52
	v_sqrt_f32_e32 v52, v52
	v_add_f32_e32 v14, 1.0, v14
	v_rcp_f32_e32 v14, v14
	s_waitcnt lgkmcnt(0)
	v_lshlrev_b32_e32 v13, 16, v13
	v_add_u32_e32 v141, 64, v72
	v_mul_f32_e32 v14, v14, v52
	v_mul_f32_e32 v13, v14, v13
	v_add_f32_e32 v14, v5, v57
	v_mul_f32_e32 v14, 0xbfb8aa3b, v14
	v_exp_f32_e32 v14, v14
	ds_write2st64_b32 v141, v15, v13 offset0:136 offset1:169
	ds_read_u16 v13, v113 offset:34
	v_add_f32_e32 v14, 1.0, v14
	v_rcp_f32_e64 v14, -v14
	s_nop 0
	v_mul_f32_e32 v14, v98, v14
	v_mul_f32_e32 v15, 0x3fb8aa3b, v14
	v_exp_f32_e32 v15, v15
	v_add_f32_e32 v14, v14, v14
	v_cmp_nlt_f32_e64 s[52:53], s29, v14
	s_and_saveexec_b64 s[4:5], s[52:53]
	s_xor_b64 s[4:5], exec, s[4:5]
	v_fma_f32 v52, -v15, v15, 1.0
	s_andn2_saveexec_b64 s[4:5], s[4:5]
	v_pk_mul_f32 v[56:57], v[14:15], s[88:89] op_sel_hi:[0,1]
	v_add_f32_e32 v52, 1.0, v57
	v_fma_f32 v52, v56, v52, 1.0
	v_mul_f32_e64 v52, v52, -v14
	s_or_b64 exec, exec, s[4:5]
	v_add_f32_e32 v14, v17, v53
	v_mul_f32_e32 v14, 0xbfb8aa3b, v14
	v_exp_f32_e32 v14, v14
	v_max_f32_e32 v52, v52, v52
	v_max_f32_e32 v52, 0, v52
	v_sqrt_f32_e32 v52, v52
	v_add_f32_e32 v14, 1.0, v14
	v_rcp_f32_e32 v14, v14
	s_waitcnt lgkmcnt(0)
	v_lshlrev_b32_e32 v13, 16, v13
	v_add_u32_e32 v142, 0x44, v72
	v_mul_f32_e32 v14, v14, v52
	v_mul_f32_e32 v13, v14, v13
	v_add_f32_e32 v14, v6, v58
	v_mul_f32_e32 v14, 0xbfb8aa3b, v14
	v_exp_f32_e32 v14, v14
	ds_write2st64_b32 v142, v15, v13 offset0:136 offset1:169
	ds_read_u16 v13, v113 offset:36
	v_add_f32_e32 v14, 1.0, v14
	v_rcp_f32_e64 v14, -v14
	s_nop 0
	v_mul_f32_e32 v14, v99, v14
	v_mul_f32_e32 v15, 0x3fb8aa3b, v14
	v_exp_f32_e32 v15, v15
	v_add_f32_e32 v14, v14, v14
	v_cmp_nlt_f32_e64 s[52:53], s29, v14
	s_and_saveexec_b64 s[4:5], s[52:53]
	s_xor_b64 s[4:5], exec, s[4:5]
	v_fma_f32 v52, -v15, v15, 1.0
	s_andn2_saveexec_b64 s[4:5], s[4:5]
	v_pk_mul_f32 v[52:53], v[14:15], s[88:89] op_sel_hi:[0,1]
	v_add_f32_e32 v53, 1.0, v53
	v_fma_f32 v52, v52, v53, 1.0
	v_mul_f32_e64 v52, v52, -v14
	s_or_b64 exec, exec, s[4:5]
	v_add_f32_e32 v14, v18, v54
	v_mul_f32_e32 v14, 0xbfb8aa3b, v14
	v_exp_f32_e32 v14, v14
	v_max_f32_e32 v52, v52, v52
	v_max_f32_e32 v52, 0, v52
	v_sqrt_f32_e32 v52, v52
	v_add_f32_e32 v14, 1.0, v14
	v_rcp_f32_e32 v14, v14
	s_waitcnt lgkmcnt(0)
	v_lshlrev_b32_e32 v13, 16, v13
	v_add_u32_e32 v144, 0x48, v72
	v_mul_f32_e32 v14, v14, v52
	v_mul_f32_e32 v13, v14, v13
	v_add_f32_e32 v14, v7, v59
	v_mul_f32_e32 v14, 0xbfb8aa3b, v14
	v_exp_f32_e32 v14, v14
	ds_write2st64_b32 v144, v15, v13 offset0:136 offset1:169
	ds_read_u16 v13, v113 offset:38
	v_add_f32_e32 v14, 1.0, v14
	v_rcp_f32_e64 v14, -v14
	s_nop 0
	v_mul_f32_e32 v14, v105, v14
	v_mul_f32_e32 v15, 0x3fb8aa3b, v14
	v_exp_f32_e32 v15, v15
	v_add_f32_e32 v14, v14, v14
	v_cmp_nlt_f32_e64 s[52:53], s29, v14
	s_and_saveexec_b64 s[4:5], s[52:53]
	s_xor_b64 s[4:5], exec, s[4:5]
	v_fma_f32 v52, -v15, v15, 1.0
	s_andn2_saveexec_b64 s[4:5], s[4:5]
	v_pk_mul_f32 v[52:53], v[14:15], s[88:89] op_sel_hi:[0,1]
	v_add_f32_e32 v53, 1.0, v53
	v_fma_f32 v52, v52, v53, 1.0
	v_mul_f32_e64 v52, v52, -v14
	s_or_b64 exec, exec, s[4:5]
	v_add_f32_e32 v14, v19, v55
	v_mul_f32_e32 v14, 0xbfb8aa3b, v14
	v_exp_f32_e32 v14, v14
	v_max_f32_e32 v52, v52, v52
	v_max_f32_e32 v52, 0, v52
	v_sqrt_f32_e32 v52, v52
	v_add_f32_e32 v14, 1.0, v14
	v_rcp_f32_e32 v14, v14
	s_waitcnt lgkmcnt(0)
	v_lshlrev_b32_e32 v13, 16, v13
	v_add_u32_e32 v145, 0x4c, v72
	v_add_u32_e32 v137, 0x8800, v114
	v_mul_f32_e32 v14, v14, v52
	v_mul_f32_e32 v13, v14, v13
	v_add_u32_e32 v138, 0xa800, v114
	ds_write2st64_b32 v145, v15, v13 offset0:136 offset1:169
	s_waitcnt lgkmcnt(0)
	s_barrier
; __device__ __forceinline__ void rglru_unit(const Params& p, const WS& ws, int j, int u, bool dry = false) {
;     ...
;     {
;       float A = 1.f, Hh = 0.f;
; #pragma unroll
;       for (int i = 0; i < 8; ++i) {
;         const float a = AUa[(8 * ssg + i) * 33 + sc], uu = AUu[(8 * ssg + i) * 33 + sc];
;         Hh = a * Hh + uu; A *= a;
;       }
;       SEGA[ssg * 32 + sc] = A; SEGH[ssg * 32 + sc] = Hh;
;     }
;     __syncthreads();
;     float hin = CARRY[sc];
; #pragma unroll
;     for (int s2 = 0; s2 < 7; ++s2)
;       if (s2 < ssg) hin = SEGA[s2 * 32 + sc] * hin + SEGH[s2 * 32 + sc];
	ds_read2_b32 v[14:15], v137 offset1:33
	ds_read2_b32 v[52:53], v138 offset0:64 offset1:97
	v_add_u32_e32 v140, 0xac00, v114
	s_waitcnt lgkmcnt(0)
	v_fma_f32 v13, 0, v14, v52
	v_fmac_f32_e32 v53, v13, v15
	v_mul_f32_e32 v13, v14, v15
	ds_read2_b32 v[14:15], v137 offset0:66 offset1:99
	ds_read2_b32 v[54:55], v138 offset0:130 offset1:163
	s_waitcnt lgkmcnt(1)
	v_mul_f32_e32 v13, v13, v14
	s_waitcnt lgkmcnt(0)
	v_fma_f32 v52, v53, v14, v54
	v_fmac_f32_e32 v55, v52, v15
	v_mul_f32_e32 v13, v13, v15
	ds_read2_b32 v[14:15], v137 offset0:132 offset1:165
	ds_read2_b32 v[52:53], v138 offset0:196 offset1:229
	s_waitcnt lgkmcnt(1)
	v_mul_f32_e32 v13, v13, v14
	s_waitcnt lgkmcnt(0)
	v_fma_f32 v52, v55, v14, v52
	v_fmac_f32_e32 v53, v52, v15
	v_mul_f32_e32 v13, v13, v15
	ds_read2_b32 v[14:15], v137 offset0:198 offset1:231
	ds_read2_b32 v[54:55], v140 offset0:6 offset1:39
	s_waitcnt lgkmcnt(1)
	v_mul_f32_e32 v13, v13, v14
	s_waitcnt lgkmcnt(0)
	v_fma_f32 v52, v53, v14, v54
	v_fmac_f32_e32 v55, v52, v15
	v_mul_f32_e32 v13, v13, v15
	ds_write2st64_b32 v78, v13, v55 offset0:202 offset1:206
	s_waitcnt lgkmcnt(0)
	s_barrier
	ds_read_b32 v13, v115 offset:53760
	s_and_saveexec_b64 s[4:5], vcc
	s_cbranch_execz .LBB0_1548
	ds_read2st64_b32 v[14:15], v115 offset0:202 offset1:206
	s_waitcnt lgkmcnt(0)
	v_fmac_f32_e32 v15, v13, v14
	v_mov_b32_e32 v13, v15
	s_or_b64 exec, exec, s[4:5]
	v_add_u32_e32 v143, 0x80, v115
	s_and_saveexec_b64 s[4:5], s[38:39]
	s_cbranch_execnz .LBB0_1549

; __device__ __forceinline__ float bf2f(bf16_t v) { return __uint_as_float(((unsigned)v) << 16); }
; __device__ __forceinline__ float sigmoidf_(float x) { return __builtin_amdgcn_rcpf(1.f + __expf(-x)); }
; #define MFMA16(a, b, c) __builtin_amdgcn_mfma_f32_16x16x32_bf16((a), (b), (c), 0, 0, 0)
; __device__ __forceinline__ void rglru_unit(const Params& p, const WS& ws, int j, int u, bool dry = false) {
;     ...
; #pragma unroll
;       for (int ks = 0; ks < 4; ++ks) {
;         const bf16x8 xf = *(const bf16x8*)(XC + (16 * w + lr) * 136 + 32 * ks + 8 * lq);
; #pragma unroll
;         for (int gate = 0; gate < 2; ++gate)
; #pragma unroll
;           for (int mt = 0; mt < 2; ++mt) {
;             const bf16x8 wf = *(const bf16x8*)(WG + (gate * 32 + 16 * mt + lr) * 136 + 32 * ks + 8 * lq);
;             ga_[gate][mt] = MFMA16(wf, xf, ga_[gate][mt]);
;           }
;       }
;       const int tok = 16 * w + lr;
; #pragma unroll
;       for (int mt = 0; mt < 2; ++mt)
; #pragma unroll
;         for (int jj = 0; jj < 4; ++jj) {
;           const int n = 16 * mt + 4 * lq + jj;
;           const float xcv = bf2f(XC[tok * 136 + 32 * jq + n]);
;           const float r = sigmoidf_(ga_[0][mt][jj] + ba[mt][jj]);
;           const float ig = sigmoidf_(ga_[1][mt][jj] + bx[mt][jj]);
;           const float la = -r * sp[mt][jj];
;           const float a = __expf(la);
;           const float x2 = 2.f * la;
;           const float om = x2 > -0.02f ? -x2 * (1.f + 0.5f * x2 * (1.f + x2 * (1.f / 3.f))) : 1.f - a * a;
;           const float mult = __builtin_amdgcn_sqrtf(fmaxf(om, 0.f));
;           AUa[tok * 33 + n] = a;
;           AUu[tok * 33 + n] = mult * ig * xcv;
;         }
.LBB0_1505:
	ds_read_b128 v[52:55], v111
	ds_read_b128 v[56:59], v112 offset:17408
	ds_read_b128 v[60:63], v112 offset:21760
	ds_read_b128 v[64:67], v112 offset:26112
	ds_read_b128 v[120:123], v112 offset:30464
	ds_read_b128 v[212:215], v111 offset:64
	ds_read_b128 v[216:219], v111 offset:128
	ds_read_b128 v[220:223], v111 offset:192
	ds_read_b128 v[224:227], v112 offset:17472
	ds_read_b128 v[228:231], v112 offset:21824
	ds_read_b128 v[232:235], v112 offset:26176
	ds_read_b128 v[244:247], v112 offset:30528
	ds_read_b128 v[248:251], v112 offset:17536
	ds_read_b128 v[252:255], v112 offset:21888
	s_waitcnt lgkmcnt(12)
	v_mfma_f32_16x16x32_bf16 v[56:59], v[56:59], v[52:55], 0
	s_waitcnt lgkmcnt(11)
	v_mfma_f32_16x16x32_bf16 v[60:63], v[60:63], v[52:55], 0
	s_waitcnt lgkmcnt(10)
	v_mfma_f32_16x16x32_bf16 v[64:67], v[64:67], v[52:55], 0
	s_waitcnt lgkmcnt(9)
	v_mfma_f32_16x16x32_bf16 v[52:55], v[120:123], v[52:55], 0
	s_nop 0
	s_nop 0
	s_waitcnt lgkmcnt(5)
	v_mfma_f32_16x16x32_bf16 v[56:59], v[224:227], v[212:215], v[56:59]
	ds_read_b128 v[224:227], v112 offset:26240
	s_nop 0
	s_waitcnt lgkmcnt(5)
	v_mfma_f32_16x16x32_bf16 v[60:63], v[228:231], v[212:215], v[60:63]
	ds_read_b128 v[228:231], v112 offset:30592
	s_nop 0
	s_waitcnt lgkmcnt(5)
	v_mfma_f32_16x16x32_bf16 v[64:67], v[232:235], v[212:215], v[64:67]
	ds_read_b128 v[232:235], v112 offset:17600
	s_nop 0
	s_waitcnt lgkmcnt(5)
	v_mfma_f32_16x16x32_bf16 v[52:55], v[244:247], v[212:215], v[52:55]
	ds_read_b128 v[244:247], v112 offset:21952
	s_nop 0
	s_nop 0
	s_waitcnt lgkmcnt(5)
	v_mfma_f32_16x16x32_bf16 v[56:59], v[248:251], v[216:219], v[56:59]
	ds_read_b128 v[248:251], v112 offset:26304
	s_nop 0
	s_waitcnt lgkmcnt(5)
	v_mfma_f32_16x16x32_bf16 v[60:63], v[252:255], v[216:219], v[60:63]
	ds_read_b128 v[252:255], v112 offset:30656
	s_nop 0
	s_waitcnt lgkmcnt(5)
	v_mfma_f32_16x16x32_bf16 v[154:157], v[224:227], v[216:219], v[64:67]
	s_nop 2
	s_nop 0
	s_waitcnt lgkmcnt(4)
	v_mfma_f32_16x16x32_bf16 v[52:55], v[228:231], v[216:219], v[52:55]
	s_nop 0
	s_nop 0
	ds_read_u16 v15, v113
	s_waitcnt lgkmcnt(4)
	v_mfma_f32_16x16x32_bf16 v[64:67], v[232:235], v[220:223], v[56:59]
	s_nop 2
	s_nop 0
	s_waitcnt lgkmcnt(3)
	v_mfma_f32_16x16x32_bf16 v[56:59], v[244:247], v[220:223], v[60:63]
	s_nop 2
	s_nop 0
	v_add_f32_e32 v14, v0, v64
	v_mul_f32_e32 v14, 0xbfb8aa3b, v14
	v_exp_f32_e32 v14, v14
	s_waitcnt lgkmcnt(2)
	v_mfma_f32_16x16x32_bf16 v[60:63], v[248:251], v[220:223], v[154:157]
	s_nop 2
	s_nop 0
	v_add_f32_e32 v14, 1.0, v14
	v_rcp_f32_e64 v14, -v14
	s_waitcnt lgkmcnt(0)
	v_mfma_f32_16x16x32_bf16 v[52:55], v[252:255], v[220:223], v[52:55]
	v_mul_f32_e32 v14, v89, v14
	v_mul_f32_e32 v64, 0x3fb8aa3b, v14
	v_exp_f32_e32 v64, v64
	v_add_f32_e32 v14, v14, v14
	v_cmp_nlt_f32_e64 s[52:53], s29, v14
	s_and_saveexec_b64 s[4:5], s[52:53]
	s_xor_b64 s[4:5], exec, s[4:5]
	v_fma_f32 v119, -v64, v64, 1.0
	s_andn2_saveexec_b64 s[4:5], s[4:5]
	v_pk_mul_f32 v[120:121], v[14:15], s[88:89] op_sel_hi:[0,1]
	v_add_f32_e32 v119, 1.0, v121
	v_fma_f32 v119, v120, v119, 1.0
	v_mul_f32_e64 v119, v119, -v14
	s_or_b64 exec, exec, s[4:5]
	v_add_f32_e32 v14, v8, v60
	v_add_f32_e32 v65, v1, v65
	v_mul_f32_e32 v14, 0xbfb8aa3b, v14
	v_mul_f32_e32 v65, 0xbfb8aa3b, v65
	v_exp_f32_e32 v14, v14
	v_exp_f32_e32 v65, v65
	v_max_f32_e32 v60, v119, v119
	v_max_f32_e32 v60, 0, v60
	v_add_f32_e32 v14, 1.0, v14
	v_add_f32_e32 v65, 1.0, v65
	v_rcp_f32_e32 v14, v14
	v_sqrt_f32_e32 v60, v60
	v_rcp_f32_e64 v65, -v65
	v_lshlrev_b32_e32 v15, 16, v15
	v_mul_f32_e32 v14, v14, v60
	v_mul_f32_e32 v65, v93, v65
	v_mul_f32_e32 v14, v14, v15
	ds_read_u16 v60, v113 offset:2
	v_mul_f32_e32 v15, 0x3fb8aa3b, v65
	v_exp_f32_e32 v15, v15
	ds_write2st64_b32 v72, v64, v14 offset0:136 offset1:169
	v_add_f32_e32 v14, v65, v65
	v_cmp_nlt_f32_e64 s[52:53], s29, v14
	s_and_saveexec_b64 s[4:5], s[52:53]
	s_xor_b64 s[4:5], exec, s[4:5]
	v_fma_f32 v64, -v15, v15, 1.0
	s_andn2_saveexec_b64 s[4:5], s[4:5]
	v_pk_mul_f32 v[64:65], v[14:15], s[88:89] op_sel_hi:[0,1]
	v_add_f32_e32 v65, 1.0, v65
	v_fma_f32 v64, v64, v65, 1.0
	v_mul_f32_e64 v64, v64, -v14
	s_or_b64 exec, exec, s[4:5]
	v_add_f32_e32 v14, v9, v61
	v_max_f32_e32 v61, v64, v64
	v_add_f32_e32 v64, v2, v66
	v_mul_f32_e32 v14, 0xbfb8aa3b, v14
	v_mul_f32_e32 v64, 0xbfb8aa3b, v64
	v_exp_f32_e32 v14, v14
	v_exp_f32_e32 v64, v64
	v_max_f32_e32 v61, 0, v61
	v_sqrt_f32_e32 v61, v61
	v_add_f32_e32 v14, 1.0, v14
	v_add_f32_e32 v64, 1.0, v64
	v_rcp_f32_e32 v14, v14
	v_rcp_f32_e64 v64, -v64
	s_waitcnt lgkmcnt(1)
	v_lshlrev_b32_e32 v60, 16, v60
	v_mul_f32_e32 v14, v14, v61
	v_mul_f32_e32 v64, v95, v64
	v_mul_f32_e32 v14, v14, v60
	ds_read_u16 v61, v113 offset:4
	v_mul_f32_e32 v60, 0x3fb8aa3b, v64
	v_exp_f32_e32 v60, v60
	ds_write2st64_b32 v135, v15, v14 offset0:136 offset1:169
	v_add_f32_e32 v14, v64, v64
	v_cmp_nlt_f32_e64 s[52:53], s29, v14
	s_and_saveexec_b64 s[4:5], s[52:53]
	s_xor_b64 s[4:5], exec, s[4:5]
	v_fma_f32 v15, -v60, v60, 1.0
	s_andn2_saveexec_b64 s[4:5], s[4:5]
	v_pk_mul_f32 v[64:65], v[14:15], s[88:89] op_sel_hi:[0,1]
	v_add_f32_e32 v15, 1.0, v65
	v_fma_f32 v15, v64, v15, 1.0
	v_mul_f32_e64 v15, v15, -v14
	s_or_b64 exec, exec, s[4:5]
	v_add_f32_e32 v14, v10, v62
	v_add_f32_e32 v62, v3, v67
	v_mul_f32_e32 v14, 0xbfb8aa3b, v14
	v_mul_f32_e32 v62, 0xbfb8aa3b, v62
	v_exp_f32_e32 v14, v14
	v_exp_f32_e32 v62, v62
	v_max_f32_e32 v15, v15, v15
	v_max_f32_e32 v15, 0, v15
	v_add_f32_e32 v14, 1.0, v14
	v_add_f32_e32 v62, 1.0, v62
	v_rcp_f32_e32 v14, v14
	v_sqrt_f32_e32 v15, v15
	v_rcp_f32_e64 v62, -v62
	s_waitcnt lgkmcnt(1)
; __device__ __forceinline__ float bf2f(bf16_t v) { return __uint_as_float(((unsigned)v) << 16); }
; __device__ __forceinline__ float sigmoidf_(float x) { return __builtin_amdgcn_rcpf(1.f + __expf(-x)); }
; __device__ __forceinline__ void rglru_unit(const Params& p, const WS& ws, int j, int u, bool dry = false) {
;     ...
; #pragma unroll
;       for (int mt = 0; mt < 2; ++mt)
; #pragma unroll
;         for (int jj = 0; jj < 4; ++jj) {
;           const int n = 16 * mt + 4 * lq + jj;
;           const float xcv = bf2f(XC[tok * 136 + 32 * jq + n]);
;           const float r = sigmoidf_(ga_[0][mt][jj] + ba[mt][jj]);
;           const float ig = sigmoidf_(ga_[1][mt][jj] + bx[mt][jj]);
;           const float la = -r * sp[mt][jj];
;           const float a = __expf(la);
;           const float x2 = 2.f * la;
;           const float om = x2 > -0.02f ? -x2 * (1.f + 0.5f * x2 * (1.f + x2 * (1.f / 3.f))) : 1.f - a * a;
;           const float mult = __builtin_amdgcn_sqrtf(fmaxf(om, 0.f));
;           AUa[tok * 33 + n] = a;
;           AUu[tok * 33 + n] = mult * ig * xcv;
;         }
;     }
;     __syncthreads();
;     {
;       float A = 1.f, Hh = 0.f;
; #pragma unroll
;       for (int i = 0; i < 8; ++i) {
;         const float a = AUa[(8 * ssg + i) * 33 + sc], uu = AUu[(8 * ssg + i) * 33 + sc];
;         Hh = a * Hh + uu; A *= a;
;       }
;       SEGA[ssg * 32 + sc] = A; SEGH[ssg * 32 + sc] = Hh;
;     }
;     __syncthreads();
;     float hin = CARRY[sc];
; #pragma unroll
;     for (int s2 = 0; s2 < 7; ++s2)
;       if (s2 < ssg) hin = SEGA[s2 * 32 + sc] * hin + SEGH[s2 * 32 + sc];
	v_lshlrev_b32_e32 v61, 16, v61
	v_mul_f32_e32 v14, v14, v15
	v_mul_f32_e32 v62, v96, v62
	v_mul_f32_e32 v14, v14, v61
	ds_read_u16 v61, v113 offset:6
	v_mul_f32_e32 v15, 0x3fb8aa3b, v62
	v_exp_f32_e32 v15, v15
	ds_write2st64_b32 v136, v60, v14 offset0:136 offset1:169
	v_add_f32_e32 v14, v62, v62
	v_cmp_nlt_f32_e64 s[52:53], s29, v14
	s_and_saveexec_b64 s[4:5], s[52:53]
	s_xor_b64 s[4:5], exec, s[4:5]
	v_fma_f32 v60, -v15, v15, 1.0
	s_andn2_saveexec_b64 s[4:5], s[4:5]
	v_pk_mul_f32 v[64:65], v[14:15], s[88:89] op_sel_hi:[0,1]
	v_add_f32_e32 v60, 1.0, v65
	v_fma_f32 v60, v64, v60, 1.0
	v_mul_f32_e64 v60, v60, -v14
	s_or_b64 exec, exec, s[4:5]
	v_add_f32_e32 v14, v11, v63
	v_mul_f32_e32 v14, 0xbfb8aa3b, v14
	v_add_f32_e32 v56, v4, v56
	v_exp_f32_e32 v14, v14
	v_mul_f32_e32 v56, 0xbfb8aa3b, v56
	v_exp_f32_e32 v56, v56
	v_max_f32_e32 v60, v60, v60
	v_add_f32_e32 v14, 1.0, v14
	v_max_f32_e32 v60, 0, v60
	v_rcp_f32_e32 v14, v14
	v_sqrt_f32_e32 v60, v60
	v_add_f32_e32 v56, 1.0, v56
	v_rcp_f32_e64 v56, -v56
	s_waitcnt lgkmcnt(1)
	v_lshlrev_b32_e32 v61, 16, v61
	v_mul_f32_e32 v14, v14, v60
	v_mul_f32_e32 v14, v14, v61
	v_mul_f32_e32 v61, v97, v56
	ds_read_u16 v60, v113 offset:32
	v_mul_f32_e32 v56, 0x3fb8aa3b, v61
	v_exp_f32_e32 v56, v56
	ds_write2st64_b32 v139, v15, v14 offset0:136 offset1:169
	v_add_f32_e32 v14, v61, v61
	v_cmp_nlt_f32_e64 s[52:53], s29, v14
	s_and_saveexec_b64 s[4:5], s[52:53]
	s_xor_b64 s[4:5], exec, s[4:5]
	v_fma_f32 v15, -v56, v56, 1.0
	s_andn2_saveexec_b64 s[4:5], s[4:5]
	v_pk_mul_f32 v[62:63], v[14:15], s[88:89] op_sel_hi:[0,1]
	v_add_f32_e32 v15, 1.0, v63
	v_fma_f32 v15, v62, v15, 1.0
	v_mul_f32_e64 v15, v15, -v14
	s_or_b64 exec, exec, s[4:5]
	v_add_f32_e32 v14, v16, v52
	v_mul_f32_e32 v14, 0xbfb8aa3b, v14
	v_add_f32_e32 v52, v5, v57
	v_exp_f32_e32 v14, v14
	v_mul_f32_e32 v52, 0xbfb8aa3b, v52
	v_exp_f32_e32 v52, v52
	v_max_f32_e32 v15, v15, v15
	v_add_f32_e32 v14, 1.0, v14
	v_max_f32_e32 v15, 0, v15
	v_rcp_f32_e32 v14, v14
	v_sqrt_f32_e32 v15, v15
	v_add_f32_e32 v52, 1.0, v52
	s_waitcnt lgkmcnt(1)
	v_lshlrev_b32_e32 v57, 16, v60
	v_rcp_f32_e64 v60, -v52
	v_mul_f32_e32 v14, v14, v15
	v_mul_f32_e32 v14, v14, v57
	ds_read_u16 v52, v113 offset:34
	v_mul_f32_e32 v57, v98, v60
	v_mul_f32_e32 v15, 0x3fb8aa3b, v57
	v_exp_f32_e32 v15, v15
	ds_write2st64_b32 v141, v56, v14 offset0:136 offset1:169
	v_add_f32_e32 v14, v57, v57
	v_cmp_nlt_f32_e64 s[52:53], s29, v14
	s_and_saveexec_b64 s[4:5], s[52:53]
	s_xor_b64 s[4:5], exec, s[4:5]
	v_fma_f32 v56, -v15, v15, 1.0
	s_andn2_saveexec_b64 s[4:5], s[4:5]
	v_pk_mul_f32 v[56:57], v[14:15], s[88:89] op_sel_hi:[0,1]
	v_add_f32_e32 v57, 1.0, v57
	v_fma_f32 v56, v56, v57, 1.0
	v_mul_f32_e64 v56, v56, -v14
	s_or_b64 exec, exec, s[4:5]
	v_add_f32_e32 v14, v17, v53
	v_max_f32_e32 v53, v56, v56
	v_add_f32_e32 v56, v6, v58
	v_mul_f32_e32 v14, 0xbfb8aa3b, v14
	v_mul_f32_e32 v56, 0xbfb8aa3b, v56
	v_exp_f32_e32 v14, v14
	v_exp_f32_e32 v56, v56
	v_max_f32_e32 v53, 0, v53
	v_sqrt_f32_e32 v53, v53
	v_add_f32_e32 v14, 1.0, v14
	v_add_f32_e32 v56, 1.0, v56
	v_rcp_f32_e32 v14, v14
	v_rcp_f32_e64 v56, -v56
	s_waitcnt lgkmcnt(1)
	v_lshlrev_b32_e32 v52, 16, v52
	v_mul_f32_e32 v14, v14, v53
	v_mul_f32_e32 v56, v99, v56
	v_mul_f32_e32 v14, v14, v52
	ds_read_u16 v53, v113 offset:36
	v_mul_f32_e32 v52, 0x3fb8aa3b, v56
	v_exp_f32_e32 v52, v52
	ds_write2st64_b32 v142, v15, v14 offset0:136 offset1:169
	v_add_f32_e32 v14, v56, v56
	v_cmp_nlt_f32_e64 s[52:53], s29, v14
	s_and_saveexec_b64 s[4:5], s[52:53]
	s_xor_b64 s[4:5], exec, s[4:5]
	v_fma_f32 v15, -v52, v52, 1.0
	s_andn2_saveexec_b64 s[4:5], s[4:5]
	v_pk_mul_f32 v[56:57], v[14:15], s[88:89] op_sel_hi:[0,1]
	v_add_f32_e32 v15, 1.0, v57
	v_fma_f32 v15, v56, v15, 1.0
	v_mul_f32_e64 v15, v15, -v14
	s_or_b64 exec, exec, s[4:5]
	v_add_f32_e32 v14, v18, v54
	v_add_f32_e32 v54, v7, v59
	v_mul_f32_e32 v14, 0xbfb8aa3b, v14
	v_mul_f32_e32 v54, 0xbfb8aa3b, v54
	v_exp_f32_e32 v14, v14
	v_exp_f32_e32 v54, v54
	v_max_f32_e32 v15, v15, v15
	v_max_f32_e32 v15, 0, v15
	v_add_f32_e32 v14, 1.0, v14
	v_add_f32_e32 v54, 1.0, v54
	v_rcp_f32_e32 v14, v14
	v_sqrt_f32_e32 v15, v15
	v_rcp_f32_e64 v54, -v54
	s_waitcnt lgkmcnt(1)
	v_lshlrev_b32_e32 v53, 16, v53
	v_mul_f32_e32 v14, v14, v15
	v_mul_f32_e32 v54, v105, v54
	v_mul_f32_e32 v14, v14, v53
	ds_read_u16 v53, v113 offset:38
	v_mul_f32_e32 v15, 0x3fb8aa3b, v54
	v_exp_f32_e32 v15, v15
	ds_write2st64_b32 v144, v52, v14 offset0:136 offset1:169
	v_add_f32_e32 v14, v54, v54
	v_cmp_nlt_f32_e64 s[52:53], s29, v14
	s_and_saveexec_b64 s[4:5], s[52:53]
	s_xor_b64 s[4:5], exec, s[4:5]
	v_fma_f32 v52, -v15, v15, 1.0
	s_andn2_saveexec_b64 s[4:5], s[4:5]
	v_pk_mul_f32 v[56:57], v[14:15], s[88:89] op_sel_hi:[0,1]
	v_add_f32_e32 v52, 1.0, v57
	v_fma_f32 v52, v56, v52, 1.0
	v_mul_f32_e64 v52, v52, -v14
	s_or_b64 exec, exec, s[4:5]
	s_waitcnt lgkmcnt(1)
	v_lshlrev_b32_e32 v14, 16, v53
	v_add_f32_e32 v53, v19, v55
	v_mul_f32_e32 v53, 0xbfb8aa3b, v53
	v_exp_f32_e32 v53, v53
	v_max_f32_e32 v52, v52, v52
	v_max_f32_e32 v52, 0, v52
	v_sqrt_f32_e32 v52, v52
	v_add_f32_e32 v53, 1.0, v53
	v_rcp_f32_e32 v53, v53
	s_nop 0
	v_mul_f32_e32 v52, v53, v52
	v_mul_f32_e32 v14, v52, v14
	ds_write2st64_b32 v145, v15, v14 offset0:136 offset1:169
	s_waitcnt lgkmcnt(0)
	s_barrier
	ds_read2_b32 v[14:15], v137 offset1:33
	ds_read2_b32 v[52:53], v138 offset0:64 offset1:97
	s_waitcnt lgkmcnt(0)
	v_fma_f32 v52, 0, v14, v52
	v_fmac_f32_e32 v53, v52, v15
	v_mul_f32_e32 v52, v14, v15
	ds_read2_b32 v[14:15], v137 offset0:66 offset1:99
	ds_read2_b32 v[54:55], v138 offset0:130 offset1:163
	s_waitcnt lgkmcnt(0)
	v_fma_f32 v53, v53, v14, v54
	v_mul_f32_e32 v14, v52, v14
	v_fmac_f32_e32 v55, v53, v15
	v_mul_f32_e32 v54, v14, v15
	ds_read2_b32 v[14:15], v137 offset0:132 offset1:165
	ds_read2_b32 v[52:53], v138 offset0:196 offset1:229
	s_waitcnt lgkmcnt(0)
	v_fma_f32 v52, v55, v14, v52
	v_mul_f32_e32 v14, v54, v14
	v_fmac_f32_e32 v53, v52, v15
	v_mul_f32_e32 v52, v14, v15
	ds_read2_b32 v[14:15], v137 offset0:198 offset1:231
	ds_read2_b32 v[54:55], v140 offset0:6 offset1:39
	s_waitcnt lgkmcnt(0)
	v_fma_f32 v53, v53, v14, v54
	v_mul_f32_e32 v14, v52, v14
	v_fmac_f32_e32 v55, v53, v15
	v_mul_f32_e32 v14, v14, v15
	ds_write2st64_b32 v78, v14, v55 offset0:202 offset1:206
	s_waitcnt lgkmcnt(0)
	s_barrier
	ds_read_b32 v14, v115 offset:53760
	s_and_saveexec_b64 s[4:5], vcc
	s_cbranch_execz .LBB0_1557
	ds_read2st64_b32 v[52:53], v115 offset0:202 offset1:206
	s_waitcnt lgkmcnt(0)
	v_fmac_f32_e32 v53, v14, v52
	v_mov_b32_e32 v14, v53
	s_or_b64 exec, exec, s[4:5]
	s_and_saveexec_b64 s[4:5], s[38:39]
	s_cbranch_execnz .LBB0_1558
